# P2 weight conversion: three-gate-tile workgroups convert nothing; two-gate-tile workgroups start at item g, HGRN workgroups at 512+g
# baseline (speedup 1.0000x reference)
;     ...
;     { int it = (PART == 0 ? gw : I_IN + gw); const int end = (PART == 0 ? I_IN : (I_IN + it_last < NITEMS ? I_IN + it_last : NITEMS));
;       if (it < end) {
; __global__ void __launch_bounds__(NTHREADS, 2) hybrid_fwd(Args args) {
;     ...
;                 if (idx < 128) attn_mfma(args, idx * 40 + wave, 5, NWAVES); else attn_mfma(args, 5120 + (idx - 128) * 48 + wave, 6, NWAVES);
;                 if (idx < 128) p0_prologue<1>(args, lds, wave, lane, idx * NWAVES + wave, 1024, 2048);
;                 else p0_prologue<1>(args, lds, wave, lane, 2048 + (idx - 128) * NWAVES + wave, 1024);
;                 S.l0 = idx; S.l1 = 192 + idx; S.l2 = idx < 128 ? 384 + idx : -1; }
.LBB0_416:
	s_mov_b64 s[2:3], -1
	s_and_b64 vcc, exec, s[0:1]
	s_cbranch_vccz .LBB0_511
	s_lshl_b32 s0, s33, 3
	v_readlane_b32 s1, v254, 11
	s_add_i32 s0, s0, s1
	s_addk_i32 s0, 0xfa00
	s_cmpk_gt_i32 s0, 0x167f
	s_cbranch_scc1 .LBB0_510
	s_add_i32 s40, s0, 0x1200
	s_cmp_gt_i32 s0, -1
	s_cbranch_scc0 .LBB0_425
	s_cmpk_gt_u32 s40, 0x13ff
	s_cbranch_scc0 .LBB0_426
	s_cmpk_gt_u32 s40, 0x15ff
	s_cbranch_scc0 .LBB0_427
	s_cmpk_gt_u32 s40, 0x17ff
	s_cbranch_scc0 .LBB0_428
	s_cmpk_gt_u32 s40, 0x22ff
	s_cbranch_scc0 .LBB0_429
	s_add_u32 s8, s72, 0x2500000
	s_addc_u32 s9, s73, 0
	s_lshl_b32 s0, s40, 1
	s_add_i32 s0, s0, 0x7fffba00
	s_and_b32 s4, s0, 0x7fffffc0
	s_lshl_b32 s0, s40, 5
	s_and_b32 s10, s0, 0x3e0
	s_mov_b64 s[6:7], 0
	s_mov_b64 s[0:1], 0
	s_mov_b64 s[2:3], s[68:69]
	s_branch .LBB0_430

; __device__ __forceinline__ ConvItem conv_item(const Args& a, unsigned char* ws, int it) {
;     ...
;     if (r < I_SQ) { p.W = a.in[7]; p.N = 1024; p.WT = (bf16*)(ws + WS_WHS); p.ldT = 2048; p.k0 = 64 * (r / 32); p.n0d = p.n0s = 32 * (r % 32); return p; } r -= I_SQ;
;     if (r < I_SQ) { p.W = a.in[8]; p.N = 1024; p.WT = (bf16*)(ws + WS_WHS); p.ldT = 2048; p.koff = 1024; p.k0 = 64 * (r / 32); p.n0d = p.n0s = 32 * (r % 32); return p; } r -= I_SQ;
;     if (r < I_SQ) { p.W = a.in[9]; p.N = 1024; p.WT = (bf16*)(ws + WS_WO); p.ldT = 1024; p.k0 = 64 * (r / 32); p.n0d = p.n0s = 32 * (r % 32); return p; } r -= I_SQ;
;     if (r < I_F1) { const int nblk = 2 * FFH / 32, kb = r / nblk, nb = r % nblk, n0d = 32 * nb, pn = n0d >> 8, q = n0d & 255;
;         p.W = a.in[11]; p.N = 2 * FFH; p.WT = (bf16*)(ws + WS_WF1); p.ldT = 1024; p.k0 = 64 * kb; p.n0d = n0d; p.n0s = (q >> 7) * FFH + 128 * pn + (q & 127); p.ks = a.in[10]; return p; } r -= I_F1;
;     ...
;     { int it = (PART == 0 ? gw : I_IN + gw); const int end = (PART == 0 ? I_IN : (I_IN + it_last < NITEMS ? I_IN + it_last : NITEMS));
;       if (it < end) {
;         ConvItem pa = conv_item(a, ws, it), pb = pa; float wa[32], wb[32]; f32x4 ka[2], kb[2];
; __global__ void __launch_bounds__(NTHREADS, 2) hybrid_fwd(Args args) {
;     ...
;                 if (idx < 128) p0_prologue<1>(args, lds, wave, lane, idx * NWAVES + wave, 1024, 2048);
.LBB0_511:
	s_andn2_b64 vcc, exec, s[2:3]
	s_cbranch_vccnz .LBB0_546
	s_lshl_b32 s0, s46, 3
	v_readlane_b32 s1, v254, 11
	s_add_i32 s18, s1, s0
	s_cmpk_gt_i32 s18, 0xffff
	s_cbranch_scc1 .LBB0_546
	s_add_i32 s5, s18, 0x1200
	s_cmpk_gt_u32 s18, 0x1ff
	s_cselect_b64 s[14:15], -1, 0
	s_and_b64 vcc, exec, s[14:15]
	s_cbranch_vccz .LBB0_517
	s_cmpk_gt_u32 s18, 0x3ff
	s_cbranch_scc0 .LBB0_518
	s_cmpk_gt_u32 s18, 0x5ff
	s_cbranch_scc0 .LBB0_519
	s_add_i32 s0, s5, 0xe800
	s_and_b32 s1, s0, 0xffff
	s_mul_i32 s1, s1, 0xba2f
	s_lshr_b32 s1, s1, 23
	s_mul_i32 s2, s1, 0xb0
	s_sub_i32 s0, s0, s2
	s_and_b32 s4, s0, 0xffff
	s_lshl_b32 s20, s4, 5
	s_add_u32 s2, s72, 0x1a00000
	s_addc_u32 s3, s73, 0
	s_lshl_b32 s6, s1, 6
	s_bfe_i32 s0, s0, 0x10002
	s_lshl_b32 s1, s4, 4
	s_and_b32 s0, s0, 0xb00
	s_and_b32 s1, s1, 0xf80
	v_readlane_b32 s24, v254, 0
	s_add_i32 s0, s0, s1
	s_and_b32 s1, s20, 0x60
	v_readlane_b32 s28, v254, 4
	v_readlane_b32 s29, v254, 5
	v_readlane_b32 s30, v254, 6
	v_readlane_b32 s31, v254, 7
	s_or_b32 s4, s0, s1
	s_mov_b64 s[0:1], 0
	v_readlane_b32 s25, v254, 1
	v_readlane_b32 s26, v254, 2
	v_readlane_b32 s27, v254, 3
	s_mov_b64 s[8:9], s[28:29]
	s_mov_b64 s[10:11], s[30:31]
	s_branch .LBB0_520

;     ...
;     { int it = (PART == 0 ? gw : I_IN + gw); const int end = (PART == 0 ? I_IN : (I_IN + it_last < NITEMS ? I_IN + it_last : NITEMS));
;       if (it < end) {
; __global__ void __launch_bounds__(NTHREADS, 2) hybrid_fwd(Args args) {
;     ...
;             if ((int)blockIdx.x < 64) { hgrn_v2(args, lds, (int)blockIdx.x, 64); p0_prologue<1>(args, lds, wave, lane, 2048 + 512 + (int)blockIdx.x * NWAVES + wave, 1024); S.l0 = -1; S.l1 = -1; S.l2 = -1; }
.LBB0_580:
	s_lshl_b32 s0, s33, 3
	v_readlane_b32 s1, v254, 11
	s_add_i32 s0, s0, s1
	s_addk_i32 s0, 0x200
	s_cmpk_gt_i32 s0, 0x167f
	s_cbranch_scc1 .LBB0_666
	s_add_i32 s38, s0, 0x1200
	s_cmp_gt_i32 s0, -1
	s_cbranch_scc0 .LBB0_587
	s_cmpk_gt_u32 s38, 0x13ff
	s_cbranch_scc0 .LBB0_588
	s_cmpk_gt_u32 s38, 0x15ff
	s_cbranch_scc0 .LBB0_589
	s_cmpk_gt_u32 s38, 0x17ff
	s_cbranch_scc0 .LBB0_590
	s_cmpk_gt_u32 s38, 0x22ff
	s_cbranch_scc0 .LBB0_591
	s_add_u32 s8, s72, 0x2500000
	s_addc_u32 s9, s73, 0
	s_lshl_b32 s0, s38, 1
	s_add_i32 s0, s0, 0x7fffba00
	s_and_b32 s4, s0, 0x7fffffc0
	s_lshl_b32 s0, s38, 5
	s_and_b32 s10, s0, 0x3e0
	s_mov_b64 s[6:7], 0
	s_mov_b64 s[0:1], 0
	s_mov_b64 s[2:3], s[68:69]
	s_branch .LBB0_592
